# gate_up K-loop: LDS-DMA stage rebalance (A-half-0 stage moved from the 6-piece load segment to the 2-piece one, vmcnt 8/6)
# baseline (speedup 1.0000x reference)
.LBB0_98:
	s_add_u32 s18, s44, 0xfffc0080
	s_addc_u32 s19, s45, -1
	s_add_i32 s46, 0, 0x10000
	s_cmp_eq_u32 s15, 12
	s_cselect_b32 s25, s7, s19
	s_cselect_b32 s24, s10, s18
	v_add_u32_e32 v148, s46, v150
	s_cselect_b32 s23, s5, s14
	s_cselect_b32 s22, s11, s13
	s_add_u32 s18, s44, 0xfffc0000
	s_addc_u32 s19, s45, -1
	s_add_i32 s47, 0, 0x14000
	ds_read_b128 v[156:159], v148
	ds_read_b128 v[160:163], v148 offset:1024
	ds_read_b128 v[164:167], v148 offset:2048
	ds_read_b128 v[168:171], v148 offset:3072
	v_add_u32_e32 v148, s47, v150
	ds_read_b128 v[172:175], v148
	ds_read_b128 v[176:179], v148 offset:1024
	ds_read_b128 v[180:183], v148 offset:2048
	ds_read_b128 v[184:187], v148 offset:3072
	v_lshl_add_u64 v[200:201], s[18:19], 0, v[144:145]
	v_lshl_add_u64 v[148:149], s[44:45], 0, v[144:145]
	s_mov_b32 m0, s50
	ds_read_b128 v[208:211], v155
	ds_read_b128 v[212:215], v155 offset:1024
	ds_read_b128 v[216:219], v155 offset:2048
	ds_read_b128 v[220:223], v155 offset:3072
	ds_read_b128 v[224:227], v155 offset:4096
	ds_read_b128 v[228:231], v155 offset:5120
	ds_read_b128 v[232:235], v155 offset:6144
	ds_read_b128 v[236:239], v155 offset:7168
	global_load_lds_dwordx4 v[200:201], off
	v_lshl_add_u64 v[200:201], s[18:19], 0, v[146:147]
	s_mov_b32 m0, s51
	s_nop 0
	global_load_lds_dwordx4 v[200:201], off
	s_add_i32 m0, s29, 0xc000
	s_nop 0
	global_load_lds_dwordx4 v[148:149], off
	v_lshl_add_u64 v[148:149], s[44:45], 0, v[146:147]
	s_add_i32 m0, s29, 0xe000
	s_nop 0
	global_load_lds_dwordx4 v[148:149], off
	s_waitcnt vmcnt(8)
	s_waitcnt lgkmcnt(0)
	s_barrier
	s_setprio 1
	s_waitcnt lgkmcnt(0)
	v_mfma_f32_16x16x32_bf16 v[128:131], v[156:159], v[208:211], v[128:131]
	v_mfma_f32_16x16x32_bf16 v[120:123], v[164:167], v[208:211], v[120:123]
	v_mfma_f32_16x16x32_bf16 v[112:115], v[156:159], v[216:219], v[112:115]
	v_mfma_f32_16x16x32_bf16 v[104:107], v[164:167], v[216:219], v[104:107]
	v_mfma_f32_16x16x32_bf16 v[96:99], v[156:159], v[224:227], v[96:99]
	v_mfma_f32_16x16x32_bf16 v[88:91], v[164:167], v[224:227], v[88:91]
	v_mfma_f32_16x16x32_bf16 v[80:83], v[156:159], v[232:235], v[80:83]
	v_mfma_f32_16x16x32_bf16 v[72:75], v[164:167], v[232:235], v[72:75]
	v_mfma_f32_16x16x32_bf16 v[128:131], v[160:163], v[212:215], v[128:131]
	v_mfma_f32_16x16x32_bf16 v[120:123], v[168:171], v[212:215], v[120:123]
	v_mfma_f32_16x16x32_bf16 v[112:115], v[160:163], v[220:223], v[112:115]
	v_mfma_f32_16x16x32_bf16 v[104:107], v[168:171], v[220:223], v[104:107]
	v_mfma_f32_16x16x32_bf16 v[96:99], v[160:163], v[228:231], v[96:99]
	v_mfma_f32_16x16x32_bf16 v[88:91], v[168:171], v[228:231], v[88:91]
	v_mfma_f32_16x16x32_bf16 v[80:83], v[160:163], v[236:239], v[80:83]
	v_mfma_f32_16x16x32_bf16 v[72:75], v[168:171], v[236:239], v[72:75]
	s_setprio 0
	s_setprio 1
	v_mfma_f32_16x16x32_bf16 v[124:127], v[172:175], v[208:211], v[124:127]
	v_mfma_f32_16x16x32_bf16 v[116:119], v[180:183], v[208:211], v[116:119]
	v_mfma_f32_16x16x32_bf16 v[108:111], v[172:175], v[216:219], v[108:111]
	v_mfma_f32_16x16x32_bf16 v[100:103], v[180:183], v[216:219], v[100:103]
	v_mfma_f32_16x16x32_bf16 v[92:95], v[172:175], v[224:227], v[92:95]
	v_mfma_f32_16x16x32_bf16 v[84:87], v[180:183], v[224:227], v[84:87]
	v_mfma_f32_16x16x32_bf16 v[76:79], v[172:175], v[232:235], v[76:79]
	v_mfma_f32_16x16x32_bf16 v[68:71], v[180:183], v[232:235], v[68:71]
	v_mfma_f32_16x16x32_bf16 v[124:127], v[176:179], v[212:215], v[124:127]
	v_mfma_f32_16x16x32_bf16 v[116:119], v[184:187], v[212:215], v[116:119]
	v_mfma_f32_16x16x32_bf16 v[108:111], v[176:179], v[220:223], v[108:111]
	v_mfma_f32_16x16x32_bf16 v[100:103], v[184:187], v[220:223], v[100:103]
	v_mfma_f32_16x16x32_bf16 v[92:95], v[176:179], v[228:231], v[92:95]
	v_mfma_f32_16x16x32_bf16 v[84:87], v[184:187], v[228:231], v[84:87]
	v_mfma_f32_16x16x32_bf16 v[76:79], v[176:179], v[236:239], v[76:79]
	v_mfma_f32_16x16x32_bf16 v[68:71], v[184:187], v[236:239], v[68:71]
	s_setprio 0
	s_barrier
	s_add_i32 s18, s46, s28
	v_lshl_add_u64 v[148:149], s[22:23], 0, v[2:3]
	s_mov_b32 m0, s18
	ds_read_b128 v[208:211], v155 offset:16384
	ds_read_b128 v[212:215], v155 offset:17408
	ds_read_b128 v[216:219], v155 offset:18432
	ds_read_b128 v[220:223], v155 offset:19456
	ds_read_b128 v[224:227], v155 offset:20480
	ds_read_b128 v[228:231], v155 offset:21504
	ds_read_b128 v[232:235], v155 offset:22528
	ds_read_b128 v[236:239], v155 offset:23552
	global_load_lds_dwordx4 v[148:149], off
	s_add_i32 m0, s18, 0x2000
	s_add_u32 s18, s22, 0x40000
	v_lshl_add_u64 v[188:189], s[22:23], 0, v[142:143]
	s_addc_u32 s19, s23, 0
	s_add_i32 s46, s47, s28
	global_load_lds_dwordx4 v[188:189], off
	v_lshl_add_u64 v[196:197], s[18:19], 0, v[2:3]
	s_mov_b32 m0, s46
	v_lshl_add_u64 v[198:199], s[24:25], 0, v[140:141]
	global_load_lds_dwordx4 v[196:197], off
	v_lshl_add_u64 v[196:197], s[18:19], 0, v[142:143]
	s_add_i32 m0, s46, 0x2000
	s_nop 0
	global_load_lds_dwordx4 v[196:197], off
	v_lshl_add_u64 v[196:197], s[24:25], 0, v[0:1]
	s_waitcnt vmcnt(6)
	s_waitcnt lgkmcnt(0)
	s_barrier
	s_setprio 1
	s_waitcnt lgkmcnt(0)
	v_mfma_f32_16x16x32_bf16 v[64:67], v[156:159], v[208:211], v[64:67]
	v_mfma_f32_16x16x32_bf16 v[56:59], v[164:167], v[208:211], v[56:59]
	v_mfma_f32_16x16x32_bf16 v[48:51], v[156:159], v[216:219], v[48:51]
	v_mfma_f32_16x16x32_bf16 v[40:43], v[164:167], v[216:219], v[40:43]
	v_mfma_f32_16x16x32_bf16 v[32:35], v[156:159], v[224:227], v[32:35]
	v_mfma_f32_16x16x32_bf16 v[24:27], v[164:167], v[224:227], v[24:27]
	v_mfma_f32_16x16x32_bf16 v[16:19], v[156:159], v[232:235], v[16:19]
	v_mfma_f32_16x16x32_bf16 v[8:11], v[164:167], v[232:235], v[8:11]
	v_mfma_f32_16x16x32_bf16 v[64:67], v[160:163], v[212:215], v[64:67]
	v_mfma_f32_16x16x32_bf16 v[56:59], v[168:171], v[212:215], v[56:59]
	v_mfma_f32_16x16x32_bf16 v[48:51], v[160:163], v[220:223], v[48:51]
	v_mfma_f32_16x16x32_bf16 v[40:43], v[168:171], v[220:223], v[40:43]
	v_mfma_f32_16x16x32_bf16 v[32:35], v[160:163], v[228:231], v[32:35]
	v_mfma_f32_16x16x32_bf16 v[24:27], v[168:171], v[228:231], v[24:27]
	v_mfma_f32_16x16x32_bf16 v[16:19], v[160:163], v[236:239], v[16:19]
	v_mfma_f32_16x16x32_bf16 v[8:11], v[168:171], v[236:239], v[8:11]
	s_setprio 0
	s_setprio 1
	v_mfma_f32_16x16x32_bf16 v[60:63], v[172:175], v[208:211], v[60:63]
	v_mfma_f32_16x16x32_bf16 v[52:55], v[180:183], v[208:211], v[52:55]
	v_mfma_f32_16x16x32_bf16 v[44:47], v[172:175], v[216:219], v[44:47]
	v_mfma_f32_16x16x32_bf16 v[36:39], v[180:183], v[216:219], v[36:39]
	v_mfma_f32_16x16x32_bf16 v[28:31], v[172:175], v[224:227], v[28:31]
	v_mfma_f32_16x16x32_bf16 v[20:23], v[180:183], v[224:227], v[20:23]
	v_mfma_f32_16x16x32_bf16 v[12:15], v[172:175], v[232:235], v[12:15]
	v_mfma_f32_16x16x32_bf16 v[4:7], v[180:183], v[232:235], v[4:7]
	v_mfma_f32_16x16x32_bf16 v[60:63], v[176:179], v[212:215], v[60:63]
	v_mfma_f32_16x16x32_bf16 v[52:55], v[184:187], v[212:215], v[52:55]
	v_mfma_f32_16x16x32_bf16 v[44:47], v[176:179], v[220:223], v[44:47]
	v_mfma_f32_16x16x32_bf16 v[36:39], v[184:187], v[220:223], v[36:39]
	v_mfma_f32_16x16x32_bf16 v[28:31], v[176:179], v[228:231], v[28:31]
	v_mfma_f32_16x16x32_bf16 v[20:23], v[184:187], v[228:231], v[20:23]
	v_mfma_f32_16x16x32_bf16 v[12:15], v[176:179], v[236:239], v[12:15]
	v_mfma_f32_16x16x32_bf16 v[4:7], v[184:187], v[236:239], v[4:7]
	s_setprio 0
	s_barrier
	s_add_i32 s46, 0, 0x18000
	s_add_i32 s47, 0, 0x1c000
	v_add_u32_e32 v168, s46, v150
	v_add_u32_e32 v184, s47, v150
	ds_read_b128 v[156:159], v168
	ds_read_b128 v[160:163], v168 offset:1024
	ds_read_b128 v[164:167], v168 offset:2048
	ds_read_b128 v[168:171], v168 offset:3072
	ds_read_b128 v[172:175], v184
	ds_read_b128 v[176:179], v184 offset:1024
	ds_read_b128 v[180:183], v184 offset:2048
	ds_read_b128 v[184:187], v184 offset:3072
	s_add_u32 s18, s24, 0x40000
	s_addc_u32 s19, s25, 0
	s_mov_b32 m0, s29
	v_lshl_add_u64 v[200:201], s[18:19], 0, v[0:1]
	ds_read_b128 v[208:211], v155 offset:32768
	ds_read_b128 v[212:215], v155 offset:33792
	ds_read_b128 v[216:219], v155 offset:34816
	ds_read_b128 v[220:223], v155 offset:35840
	ds_read_b128 v[224:227], v155 offset:36864
	ds_read_b128 v[228:231], v155 offset:37888
	ds_read_b128 v[232:235], v155 offset:38912
	ds_read_b128 v[236:239], v155 offset:39936
	global_load_lds_dwordx4 v[196:197], off
	s_mov_b32 m0, s43
	s_nop 0
	global_load_lds_dwordx4 v[198:199], off
	s_mov_b32 m0, s48
	s_nop 0
	global_load_lds_dwordx4 v[200:201], off
	v_lshl_add_u64 v[200:201], s[18:19], 0, v[140:141]
	s_mov_b32 m0, s49
	s_nop 0
	global_load_lds_dwordx4 v[200:201], off
	s_waitcnt vmcnt(8)
	s_waitcnt lgkmcnt(0)
	s_barrier
	s_setprio 1
	s_waitcnt lgkmcnt(0)
	v_mfma_f32_16x16x32_bf16 v[128:131], v[156:159], v[208:211], v[128:131]
	v_mfma_f32_16x16x32_bf16 v[120:123], v[164:167], v[208:211], v[120:123]
	v_mfma_f32_16x16x32_bf16 v[112:115], v[156:159], v[216:219], v[112:115]
	v_mfma_f32_16x16x32_bf16 v[104:107], v[164:167], v[216:219], v[104:107]
	v_mfma_f32_16x16x32_bf16 v[96:99], v[156:159], v[224:227], v[96:99]
	v_mfma_f32_16x16x32_bf16 v[88:91], v[164:167], v[224:227], v[88:91]
	v_mfma_f32_16x16x32_bf16 v[80:83], v[156:159], v[232:235], v[80:83]
	v_mfma_f32_16x16x32_bf16 v[72:75], v[164:167], v[232:235], v[72:75]
	v_mfma_f32_16x16x32_bf16 v[128:131], v[160:163], v[212:215], v[128:131]
	v_mfma_f32_16x16x32_bf16 v[120:123], v[168:171], v[212:215], v[120:123]
	v_mfma_f32_16x16x32_bf16 v[112:115], v[160:163], v[220:223], v[112:115]
	v_mfma_f32_16x16x32_bf16 v[104:107], v[168:171], v[220:223], v[104:107]
	v_mfma_f32_16x16x32_bf16 v[96:99], v[160:163], v[228:231], v[96:99]
	v_mfma_f32_16x16x32_bf16 v[88:91], v[168:171], v[228:231], v[88:91]
	v_mfma_f32_16x16x32_bf16 v[80:83], v[160:163], v[236:239], v[80:83]
	v_mfma_f32_16x16x32_bf16 v[72:75], v[168:171], v[236:239], v[72:75]
	s_setprio 0
	s_setprio 1
	v_mfma_f32_16x16x32_bf16 v[124:127], v[172:175], v[208:211], v[124:127]
	v_mfma_f32_16x16x32_bf16 v[116:119], v[180:183], v[208:211], v[116:119]
	v_mfma_f32_16x16x32_bf16 v[108:111], v[172:175], v[216:219], v[108:111]
	v_mfma_f32_16x16x32_bf16 v[100:103], v[180:183], v[216:219], v[100:103]
	v_mfma_f32_16x16x32_bf16 v[92:95], v[172:175], v[224:227], v[92:95]
	v_mfma_f32_16x16x32_bf16 v[84:87], v[180:183], v[224:227], v[84:87]
	v_mfma_f32_16x16x32_bf16 v[76:79], v[172:175], v[232:235], v[76:79]
	v_mfma_f32_16x16x32_bf16 v[68:71], v[180:183], v[232:235], v[68:71]
	v_mfma_f32_16x16x32_bf16 v[124:127], v[176:179], v[212:215], v[124:127]
	v_mfma_f32_16x16x32_bf16 v[116:119], v[184:187], v[212:215], v[116:119]
	v_mfma_f32_16x16x32_bf16 v[108:111], v[176:179], v[220:223], v[108:111]
	v_mfma_f32_16x16x32_bf16 v[100:103], v[184:187], v[220:223], v[100:103]
	v_mfma_f32_16x16x32_bf16 v[92:95], v[176:179], v[228:231], v[92:95]
	v_mfma_f32_16x16x32_bf16 v[84:87], v[184:187], v[228:231], v[84:87]
	v_mfma_f32_16x16x32_bf16 v[76:79], v[176:179], v[236:239], v[76:79]
	v_mfma_f32_16x16x32_bf16 v[68:71], v[184:187], v[236:239], v[68:71]
	s_setprio 0
	s_barrier
	s_add_i32 s18, s46, s28
	v_lshl_add_u64 v[148:149], v[148:149], 0, s[92:93]
	s_mov_b32 m0, s18
	ds_read_b128 v[208:211], v155 offset:49152
	ds_read_b128 v[212:215], v155 offset:50176
	ds_read_b128 v[216:219], v155 offset:51200
	ds_read_b128 v[220:223], v155 offset:52224
	ds_read_b128 v[224:227], v155 offset:53248
	ds_read_b128 v[228:231], v155 offset:54272
	ds_read_b128 v[232:235], v155 offset:55296
	ds_read_b128 v[236:239], v155 offset:56320
	global_load_lds_dwordx4 v[148:149], off
	s_add_i32 m0, s18, 0x2000
	s_add_u32 s18, s22, 0x40080
	v_lshl_add_u64 v[148:149], v[188:189], 0, s[92:93]
	s_addc_u32 s19, s23, 0
	s_add_i32 s22, s47, s28
	global_load_lds_dwordx4 v[148:149], off
	v_lshl_add_u64 v[148:149], s[18:19], 0, v[2:3]
	s_mov_b32 m0, s22
	s_nop 0
	global_load_lds_dwordx4 v[148:149], off
	v_lshl_add_u64 v[148:149], s[18:19], 0, v[142:143]
	s_add_i32 m0, s22, 0x2000
	s_nop 0
	global_load_lds_dwordx4 v[148:149], off
	s_waitcnt vmcnt(6)
	s_waitcnt lgkmcnt(0)
	s_barrier
	s_setprio 1
	s_waitcnt lgkmcnt(0)
	v_mfma_f32_16x16x32_bf16 v[64:67], v[156:159], v[208:211], v[64:67]
	v_mfma_f32_16x16x32_bf16 v[56:59], v[164:167], v[208:211], v[56:59]
	v_mfma_f32_16x16x32_bf16 v[48:51], v[156:159], v[216:219], v[48:51]
	v_mfma_f32_16x16x32_bf16 v[40:43], v[164:167], v[216:219], v[40:43]
	v_mfma_f32_16x16x32_bf16 v[32:35], v[156:159], v[224:227], v[32:35]
	v_mfma_f32_16x16x32_bf16 v[24:27], v[164:167], v[224:227], v[24:27]
	v_mfma_f32_16x16x32_bf16 v[16:19], v[156:159], v[232:235], v[16:19]
	v_mfma_f32_16x16x32_bf16 v[8:11], v[164:167], v[232:235], v[8:11]
	v_mfma_f32_16x16x32_bf16 v[64:67], v[160:163], v[212:215], v[64:67]
	v_mfma_f32_16x16x32_bf16 v[56:59], v[168:171], v[212:215], v[56:59]
	v_mfma_f32_16x16x32_bf16 v[48:51], v[160:163], v[220:223], v[48:51]
	v_mfma_f32_16x16x32_bf16 v[40:43], v[168:171], v[220:223], v[40:43]
	v_mfma_f32_16x16x32_bf16 v[32:35], v[160:163], v[228:231], v[32:35]
	v_mfma_f32_16x16x32_bf16 v[24:27], v[168:171], v[228:231], v[24:27]
	v_mfma_f32_16x16x32_bf16 v[16:19], v[160:163], v[236:239], v[16:19]
	v_mfma_f32_16x16x32_bf16 v[8:11], v[168:171], v[236:239], v[8:11]
	s_setprio 0
	s_setprio 1
	v_mfma_f32_16x16x32_bf16 v[60:63], v[172:175], v[208:211], v[60:63]
	v_mfma_f32_16x16x32_bf16 v[52:55], v[180:183], v[208:211], v[52:55]
	v_mfma_f32_16x16x32_bf16 v[44:47], v[172:175], v[216:219], v[44:47]
	v_mfma_f32_16x16x32_bf16 v[36:39], v[180:183], v[216:219], v[36:39]
	v_mfma_f32_16x16x32_bf16 v[28:31], v[172:175], v[224:227], v[28:31]
	v_mfma_f32_16x16x32_bf16 v[20:23], v[180:183], v[224:227], v[20:23]
	v_mfma_f32_16x16x32_bf16 v[12:15], v[172:175], v[232:235], v[12:15]
	v_mfma_f32_16x16x32_bf16 v[4:7], v[180:183], v[232:235], v[4:7]
	v_mfma_f32_16x16x32_bf16 v[60:63], v[176:179], v[212:215], v[60:63]
	v_mfma_f32_16x16x32_bf16 v[52:55], v[184:187], v[212:215], v[52:55]
	v_mfma_f32_16x16x32_bf16 v[44:47], v[176:179], v[220:223], v[44:47]
	v_mfma_f32_16x16x32_bf16 v[36:39], v[184:187], v[220:223], v[36:39]
	v_mfma_f32_16x16x32_bf16 v[28:31], v[176:179], v[228:231], v[28:31]
	v_mfma_f32_16x16x32_bf16 v[20:23], v[184:187], v[228:231], v[20:23]
	v_mfma_f32_16x16x32_bf16 v[12:15], v[176:179], v[236:239], v[12:15]
	v_mfma_f32_16x16x32_bf16 v[4:7], v[184:187], v[236:239], v[4:7]
	s_setprio 0
	s_barrier
	s_add_i32 s15, s15, 2
	s_add_u32 s44, s44, 0x100
	s_addc_u32 s45, s45, 0
	s_add_u32 s13, s13, 0x100
	s_addc_u32 s14, s14, 0
	s_cmp_gt_u32 s15, 13
	s_cbranch_scc0 .LBB0_98
	s_lshl_b32 s5, s42, 8
	s_and_b64 vcc, exec, s[2:3]
	s_cbranch_vccz .LBB0_101
	v_or_b32_e32 v148, s5, v152
	v_ashrrev_i32_e32 v149, 31, v148
	v_readlane_b32 s10, v255, 11
	v_lshlrev_b64 v[148:149], 6, v[148:149]
	v_readlane_b32 s11, v255, 12
	s_nop 1
	v_lshl_add_u64 v[148:149], s[10:11], 0, v[148:149]
	global_load_dwordx4 v[156:159], v[148:149], off
	global_load_dwordx4 v[160:163], v[148:149], off offset:32
	global_load_dwordx4 v[164:167], v[148:149], off offset:16
	global_load_dwordx4 v[168:171], v[148:149], off offset:48
	s_barrier
